# up-projection epilogue: conv weights, bias and row sums of squares of each unit staged into an LDS tail by LDS-DMA at the top of the unit K-loop; epilogue reads LDS instead of 16 global loads + vmcnt(
# speedup vs baseline: 1.0089x; 1.0067x over previous
; #define PG8_WAIT_V(n) asm volatile("s_waitcnt vmcnt(" #n ")" ::: "memory")
; #define PG8_BAR __builtin_amdgcn_s_barrier()
; template <class Epi>
; __device__ __forceinline__ void gemm_phase(LAS unsigned char* lds, const Gemm g, const StaticOrder& S, const Epi& E) {
;     ...
;     Unit cur, nxt; int ui = 0;
;     if (!S.next(0, cur)) return;
;     f32x4 acc[2][2][4][2];
; #pragma unroll
;     for (int a = 0; a < 2; ++a)
; #pragma unroll
;         for (int b = 0; b < 2; ++b)
; #pragma unroll
;             for (int m = 0; m < 4; ++m)
; #pragma unroll
;                 for (int n = 0; n < 2; ++n) acc[a][b][m][n] = (f32x4){0.f, 0.f, 0.f, 0.f};
;     bf16x8 At[4][2], B0[2][2], B1[2][2];
;     const char* cA = (const char*)g.A + (size_t)cur.pm * tstep; const char* cB = (const char*)g.Bt + (size_t)cur.pn * tstep;
;     PG8_STAGE(PG8_SB(0, 0), cB, voffB); PG8_STAGE(PG8_SA(0, 0), cA, voffA); PG8_STAGE(PG8_SB(0, 1), cB + hstep, voffB); PG8_STAGE(PG8_SA(0, 1), cA + hstep, voffA);
;     if (wr == 1) PG8_BAR;
;     PG8_WAIT_V(4); PG8_BAR;
;     PG8_STAGE(PG8_SB(1, 0), cB + kstep, voffB); PG8_STAGE(PG8_SA(1, 0), cA + kstep, voffA); PG8_STAGE(PG8_SB(1, 1), cB + hstep + kstep, voffB);
;     PG8_WAIT_V(6); PG8_BAR;
;     for (;;) {
;         const bool has_next = S.next(ui + 1, nxt);
;         const char* nA = has_next ? (const char*)g.A + (size_t)nxt.pm * tstep : cA; const char* nB = has_next ? (const char*)g.Bt + (size_t)nxt.pn * tstep : cB;
;     __device__ __forceinline__ void operator()(const f32x4 (&acc)[2][2][4][2], const Unit& u, int wr, int wc, int fr, int fq) const {
;         const int row0 = u.pm * BM + wr * 64 + fr, f0 = u.pn * HALF + wc * 32 + 8 * fq;
;         float w0[8], w1[8], w2[8], bb[8];
;         *(f32x4*)w0 = *(const f32x4*)(cw + f0); *(f32x4*)(w0 + 4) = *(const f32x4*)(cw + f0 + 4);
;         *(f32x4*)w1 = *(const f32x4*)(cw + DFF + f0); *(f32x4*)(w1 + 4) = *(const f32x4*)(cw + DFF + f0 + 4);
;         *(f32x4*)w2 = *(const f32x4*)(cw + 2 * DFF + f0); *(f32x4*)(w2 + 4) = *(const f32x4*)(cw + 2 * DFF + f0 + 4);
;         *(f32x4*)bb = *(const f32x4*)(cb + f0); *(f32x4*)(bb + 4) = *(const f32x4*)(cb + f0 + 4);
;         u64 rv[2][4];
; #pragma unroll
;         for (int ai = 0; ai < 2; ++ai)
; #pragma unroll
;             for (int m = 0; m < 4; ++m) rv[ai][m] = rss[row0 + ai * HALF + m * 16];
.LBB0_210:
	v_mov_b64_e32 v[2:3], 0x580
	s_ashr_i32 s65, s64, 31
	v_cmp_lt_i64_e32 vcc, s[52:53], v[2:3]
	s_lshl_b64 s[52:53], s[64:65], 19
	v_readlane_b32 s56, v252, 51
	v_readlane_b32 s57, v252, 52
	s_add_u32 s66, s56, s52
	s_addc_u32 s67, s57, s53
	s_and_b64 s[52:53], vcc, exec
	s_cselect_b32 s65, s67, s1
	s_cselect_b32 s96, s66, s0
	s_ashr_i32 s63, s62, 31
	s_lshl_b64 s[52:53], s[62:63], 19
	s_add_u32 s68, s50, s52
	s_addc_u32 s69, s51, s53
	s_and_b64 s[52:53], vcc, exec
	s_cselect_b32 s63, s69, s37
	s_cselect_b32 s97, s68, s36
	s_add_u32 s0, s0, 0x40080
	s_addc_u32 s1, s1, 0
	s_add_u32 vcc_lo, s36, 0x100
	v_mov_b32_e32 v6, 0
	s_addc_u32 vcc_hi, s37, 0
	s_mov_b32 s24, -2
	v_mov_b32_e32 v7, v6
	v_mov_b32_e32 v8, v6
	v_mov_b32_e32 v9, v6
	v_mov_b32_e32 v2, v6
	v_mov_b32_e32 v3, v6
	v_mov_b32_e32 v4, v6
	v_mov_b32_e32 v5, v6
	v_mov_b32_e32 v22, v6
	s_waitcnt lgkmcnt(0)
	v_mov_b32_e32 v23, v6
	v_mov_b32_e32 v24, v6
	v_mov_b32_e32 v25, v6
	v_mov_b32_e32 v18, v6
	v_mov_b32_e32 v19, v6
	v_mov_b32_e32 v20, v6
	v_mov_b32_e32 v21, v6
	v_mov_b32_e32 v38, v6
	v_mov_b32_e32 v39, v6
	v_mov_b32_e32 v40, v6
	v_mov_b32_e32 v41, v6
	v_mov_b32_e32 v34, v6
	v_mov_b32_e32 v35, v6
	v_mov_b32_e32 v36, v6
	v_mov_b32_e32 v37, v6
	v_mov_b32_e32 v82, v6
	v_mov_b32_e32 v83, v6
	v_mov_b32_e32 v84, v6
	v_mov_b32_e32 v85, v6
	v_mov_b32_e32 v86, v6
	v_mov_b32_e32 v87, v6
	v_mov_b32_e32 v88, v6
	v_mov_b32_e32 v89, v6
	v_mov_b32_e32 v10, v6
	v_mov_b32_e32 v11, v6
	v_mov_b32_e32 v12, v6
	v_mov_b32_e32 v13, v6
	v_mov_b32_e32 v14, v6
	v_mov_b32_e32 v15, v6
	v_mov_b32_e32 v16, v6
	v_mov_b32_e32 v17, v6
	v_mov_b32_e32 v26, v6
	v_mov_b32_e32 v27, v6
	v_mov_b32_e32 v28, v6
	v_mov_b32_e32 v29, v6
	v_mov_b32_e32 v30, v6
	v_mov_b32_e32 v31, v6
	v_mov_b32_e32 v32, v6
	v_mov_b32_e32 v33, v6
	v_mov_b32_e32 v66, v6
	v_mov_b32_e32 v67, v6
	v_mov_b32_e32 v68, v6
	v_mov_b32_e32 v69, v6
	v_mov_b32_e32 v78, v6
	v_mov_b32_e32 v79, v6
	v_mov_b32_e32 v80, v6
	v_mov_b32_e32 v81, v6
	v_mov_b32_e32 v90, v6
	v_mov_b32_e32 v91, v6
	v_mov_b32_e32 v92, v6
	v_mov_b32_e32 v93, v6
	v_mov_b32_e32 v94, v6
	v_mov_b32_e32 v95, v6
	v_mov_b32_e32 v96, v6
	v_mov_b32_e32 v97, v6
	v_mov_b32_e32 v102, v6
	v_mov_b32_e32 v103, v6
	v_mov_b32_e32 v104, v6
	v_mov_b32_e32 v105, v6
	v_mov_b32_e32 v98, v6
	v_mov_b32_e32 v99, v6
	v_mov_b32_e32 v100, v6
	v_mov_b32_e32 v101, v6
	v_mov_b32_e32 v118, v6
	v_mov_b32_e32 v119, v6
	v_mov_b32_e32 v120, v6
	v_mov_b32_e32 v121, v6
	v_mov_b32_e32 v114, v6
	v_mov_b32_e32 v115, v6
	v_mov_b32_e32 v116, v6
	v_mov_b32_e32 v117, v6
	v_mov_b32_e32 v134, v6
	v_mov_b32_e32 v135, v6
	v_mov_b32_e32 v136, v6
	v_mov_b32_e32 v137, v6
	v_mov_b32_e32 v130, v6
	v_mov_b32_e32 v131, v6
	v_mov_b32_e32 v132, v6
	v_mov_b32_e32 v133, v6
	v_mov_b32_e32 v146, v6
	v_mov_b32_e32 v147, v6
	v_mov_b32_e32 v148, v6
	v_mov_b32_e32 v149, v6
	v_mov_b32_e32 v150, v6
	v_mov_b32_e32 v151, v6
	v_mov_b32_e32 v152, v6
	v_mov_b32_e32 v153, v6
	v_mov_b32_e32 v106, v6
	v_mov_b32_e32 v107, v6
	v_mov_b32_e32 v108, v6
	v_mov_b32_e32 v109, v6
	v_mov_b32_e32 v110, v6
	v_mov_b32_e32 v111, v6
	v_mov_b32_e32 v112, v6
	v_mov_b32_e32 v113, v6
	v_mov_b32_e32 v122, v6
	v_mov_b32_e32 v123, v6
	v_mov_b32_e32 v124, v6
	v_mov_b32_e32 v125, v6
	v_mov_b32_e32 v126, v6
	v_mov_b32_e32 v127, v6
	v_mov_b32_e32 v128, v6
	v_mov_b32_e32 v129, v6
	v_mov_b32_e32 v138, v6
	v_mov_b32_e32 v139, v6
	v_mov_b32_e32 v140, v6
	v_mov_b32_e32 v141, v6
	v_mov_b32_e32 v142, v6
	v_mov_b32_e32 v143, v6
	v_mov_b32_e32 v144, v6
	v_mov_b32_e32 v145, v6
	v_mov_b32_e32 v154, v6
	v_mov_b32_e32 v155, v6
	v_mov_b32_e32 v156, v6
	v_mov_b32_e32 v157, v6
	v_mov_b32_e32 v158, v6
	v_mov_b32_e32 v159, v6
	v_mov_b32_e32 v160, v6
	v_mov_b32_e32 v161, v6
	s_lshr_b32 s52, s72, 6
	s_cmp_gt_u32 s52, 3
	s_cbranch_scc1 .Lst5_done
	s_and_b32 s53, s95, 1
	s_lshl_b32 s53, s53, 12
	s_lshl_b32 s56, s52, 10
	s_add_i32 s53, s53, s56
	s_add_i32 m0, s53, 0x20400
	s_cmp_gt_u32 s52, 1
	s_cbranch_scc1 .Lst5_rss
	v_and_b32_e32 v172, 31, v163
	v_lshlrev_b32_e32 v172, 4, v172
	s_lshl_b32 s56, s3, 9
	v_add_u32_e32 v172, s56, v172
	v_lshrrev_b32_e32 v173, 5, v163
	v_mul_u32_u24_e32 v174, 0x2c00, v173
	v_add_u32_e32 v174, v174, v172
	v_mov_b32_e32 v175, 0
	v_lshl_add_u64 v[190:191], s[80:81], 0, v[174:175]
	v_mov_b32_e32 v174, v172
	v_lshl_add_u64 v[192:193], s[82:83], 0, v[174:175]
	v_cmp_eq_u32_e64 s[56:57], 3, v173
	s_nop 1
	v_cndmask_b32_e64 v190, v190, v192, s[56:57]
	v_cndmask_b32_e64 v191, v191, v193, s[56:57]
	s_nop 0
	global_load_lds_dwordx4 v[190:191], off
	s_branch .Lst5_done
.Lst5_rss:
	v_add_u32_e32 v172, 0xffffff80, v163
	v_lshlrev_b32_e32 v172, 4, v172
	s_lshl_b32 s56, s2, 11
	v_add_u32_e32 v172, s56, v172
	v_mov_b32_e32 v173, 0
	v_lshl_add_u64 v[190:191], s[76:77], 0, v[172:173]
	s_nop 0
	global_load_lds_dwordx4 v[190:191], off
; #define PG8_STAGE(bufoff, gbase, voff) do { _Pragma("unroll") for (int _i = 0; _i < 2; ++_i) \
;         __builtin_amdgcn_global_load_lds((const unsigned*)((const char*)(gbase) + (voff)[_i]), (LAS unsigned*)(lds + (bufoff) + ldsw + _i * 8192), 16, 0, 0); } while (0)
; #define PG8_LDA(dst, b, h) do { _Pragma("unroll") for (int m = 0; m < 4; ++m) _Pragma("unroll") for (int k = 0; k < 2; ++k) dst[m][k] = *(const LAS bf16x8*)(lds + PG8_SA(b, h) + aoff + m * 2048 + k * 1024); } while (0)
; #define PG8_LDB(dst, b, h) do { _Pragma("unroll") for (int n = 0; n < 2; ++n) _Pragma("unroll") for (int k = 0; k < 2; ++k) dst[n][k] = *(const LAS bf16x8*)(lds + PG8_SB(b, h) + boff + n * 2048 + k * 1024); } while (0)
; #define PG8_MMA(ai, bj, At, Bt) do { __builtin_amdgcn_s_setprio(1); _Pragma("unroll") for (int m = 0; m < 4; ++m) _Pragma("unroll") for (int n = 0; n < 2; ++n) _Pragma("unroll") for (int k = 0; k < 2; ++k) \
;         acc[ai][bj][m][n] = __builtin_amdgcn_mfma_f32_16x16x32_bf16(Bt[n][k], At[m][k], acc[ai][bj][m][n], 0, 0, 0); __builtin_amdgcn_s_setprio(0); } while (0)
; #define PG8_WAIT_V(n) asm volatile("s_waitcnt vmcnt(" #n ")" ::: "memory")
; #define PG8_WAIT_L(n) asm volatile("s_waitcnt lgkmcnt(" #n ")" ::: "memory")
; template <class Epi>
; __device__ __forceinline__ void gemm_phase(LAS unsigned char* lds, const Gemm g, const StaticOrder& S, const Epi& E) {
;     ...
;         for (int t = 0; t < nt; t += 2) {
;             const bool last = (t == nt - 2);
;             const char* a1 = cA + (size_t)(t + 1) * kstep;
;             const char* a2 = last ? nA : cA + (size_t)(t + 2) * kstep; const char* b2 = last ? nB : cB + (size_t)(t + 2) * kstep;
;             const char* a3 = a2 + kstep; const char* b3 = b2 + kstep;
;             PG8_LDB(B0, 0, 0); PG8_SCHED; PG8_LDA(At, 0, 0); PG8_STAGE(PG8_SA(1, 1), a1 + hstep, voffA);
;             PG8_WAIT_L(8); PG8_BAR; PG8_WAIT_L(0); PG8_MMA(0, 0, At, B0); PG8_BAR; PG8_SCHED;
;             PG8_LDB(B1, 0, 1); PG8_STAGE(PG8_SB(0, 0), b2, voffB);
;             PG8_BAR; PG8_WAIT_L(0); PG8_MMA(0, 1, At, B1); PG8_BAR;
;             PG8_LDA(At, 0, 1); PG8_STAGE(PG8_SA(0, 0), a2, voffA);
;             PG8_BAR; PG8_WAIT_L(0); PG8_MMA(1, 0, At, B0); PG8_BAR; PG8_SCHED;
;             PG8_STAGE(PG8_SB(0, 1), b2 + hstep, voffB);
;             PG8_WAIT_V(6); PG8_BAR; PG8_MMA(1, 1, At, B1); PG8_BAR;
.Lst5_done:
.LBB0_211:
	s_add_u32 s36, s0, 0xfffc0080
	s_addc_u32 s37, s1, -1
	s_add_i32 s58, 0, 0x10000
	v_add_u32_e32 v0, s58, v171
	ds_read_b128 v[42:45], v0
	ds_read_b128 v[46:49], v0 offset:1024
	ds_read_b128 v[50:53], v0 offset:2048
	ds_read_b128 v[54:57], v0 offset:3072
	s_cmp_eq_u32 s24, 12
	s_cselect_b32 s53, s65, s37
	s_cselect_b32 s52, s96, s36
	s_cselect_b32 s37, s63, vcc_hi
	s_cselect_b32 s36, s97, vcc_lo
	v_lshl_add_u64 v[202:203], s[0:1], 0, v[186:187]
	s_add_i32 m0, s30, 0xc000
	ds_read_b128 v[58:61], v242
	ds_read_b128 v[62:65], v242 offset:1024
	ds_read_b128 v[70:73], v242 offset:2048
	ds_read_b128 v[74:77], v242 offset:3072
	ds_read_b128 v[172:175], v242 offset:4096
	ds_read_b128 v[190:193], v242 offset:5120
	ds_read_b128 v[194:197], v242 offset:6144
	ds_read_b128 v[198:201], v242 offset:7168
	global_load_lds_dwordx4 v[202:203], off
	v_lshl_add_u64 v[202:203], s[0:1], 0, v[188:189]
	s_add_i32 m0, s30, 0xe000
	s_nop 0
	global_load_lds_dwordx4 v[202:203], off
	s_waitcnt lgkmcnt(8)
	s_barrier
	s_waitcnt lgkmcnt(0)
	s_setprio 1
	s_waitcnt lgkmcnt(0)
	v_mfma_f32_16x16x32_bf16 v[158:161], v[42:45], v[58:61], v[158:161]
	v_mfma_f32_16x16x32_bf16 v[154:157], v[50:53], v[58:61], v[154:157]
	v_mfma_f32_16x16x32_bf16 v[142:145], v[42:45], v[70:73], v[142:145]
	v_mfma_f32_16x16x32_bf16 v[138:141], v[50:53], v[70:73], v[138:141]
	v_mfma_f32_16x16x32_bf16 v[126:129], v[42:45], v[172:175], v[126:129]
	v_mfma_f32_16x16x32_bf16 v[122:125], v[50:53], v[172:175], v[122:125]
	v_mfma_f32_16x16x32_bf16 v[110:113], v[42:45], v[194:197], v[110:113]
	v_mfma_f32_16x16x32_bf16 v[106:109], v[50:53], v[194:197], v[106:109]
	v_mfma_f32_16x16x32_bf16 v[158:161], v[46:49], v[62:65], v[158:161]
	v_mfma_f32_16x16x32_bf16 v[154:157], v[54:57], v[62:65], v[154:157]
	v_mfma_f32_16x16x32_bf16 v[142:145], v[46:49], v[74:77], v[142:145]
	v_mfma_f32_16x16x32_bf16 v[138:141], v[54:57], v[74:77], v[138:141]
	v_mfma_f32_16x16x32_bf16 v[126:129], v[46:49], v[190:193], v[126:129]
	v_mfma_f32_16x16x32_bf16 v[122:125], v[54:57], v[190:193], v[122:125]
	v_mfma_f32_16x16x32_bf16 v[110:113], v[46:49], v[198:201], v[110:113]
	v_mfma_f32_16x16x32_bf16 v[106:109], v[54:57], v[198:201], v[106:109]
	s_setprio 0
	s_barrier
	s_add_i32 s56, 0, 0x14000
	s_add_i32 s57, s58, s26
	v_add_u32_e32 v0, s56, v171
	v_lshl_add_u64 v[222:223], s[36:37], 0, v[180:181]
	s_mov_b32 m0, s57
	ds_read_b128 v[202:205], v0
	ds_read_b128 v[206:209], v0 offset:1024
	ds_read_b128 v[210:213], v0 offset:2048
	ds_read_b128 v[214:217], v0 offset:3072
	global_load_lds_dwordx4 v[222:223], off
	v_lshl_add_u64 v[246:247], s[36:37], 0, v[176:177]
	s_add_i32 m0, s57, 0x2000
	s_nop 0
	global_load_lds_dwordx4 v[246:247], off
	s_barrier
	s_waitcnt lgkmcnt(0)
	s_setprio 1
	s_waitcnt lgkmcnt(0)
	v_mfma_f32_16x16x32_bf16 v[150:153], v[202:205], v[58:61], v[150:153]
	v_mfma_f32_16x16x32_bf16 v[58:61], v[210:213], v[58:61], v[146:149]
	v_mfma_f32_16x16x32_bf16 v[150:153], v[206:209], v[62:65], v[150:153]
	v_mfma_f32_16x16x32_bf16 v[58:61], v[214:217], v[62:65], v[58:61]
	v_mfma_f32_16x16x32_bf16 v[62:65], v[202:205], v[70:73], v[130:133]
	v_mfma_f32_16x16x32_bf16 v[70:73], v[210:213], v[70:73], v[134:137]
	v_mfma_f32_16x16x32_bf16 v[62:65], v[206:209], v[74:77], v[62:65]
	v_mfma_f32_16x16x32_bf16 v[70:73], v[214:217], v[74:77], v[70:73]
	v_mfma_f32_16x16x32_bf16 v[74:77], v[202:205], v[172:175], v[114:117]
	v_mfma_f32_16x16x32_bf16 v[114:117], v[210:213], v[172:175], v[118:121]
	v_mfma_f32_16x16x32_bf16 v[98:101], v[202:205], v[194:197], v[98:101]
	v_mfma_f32_16x16x32_bf16 v[102:105], v[210:213], v[194:197], v[102:105]
	v_mfma_f32_16x16x32_bf16 v[118:121], v[214:217], v[190:193], v[114:117]
	v_mfma_f32_16x16x32_bf16 v[98:101], v[206:209], v[198:201], v[98:101]
	v_mfma_f32_16x16x32_bf16 v[102:105], v[214:217], v[198:201], v[102:105]
	v_mfma_f32_16x16x32_bf16 v[74:77], v[206:209], v[190:193], v[74:77]
	s_setprio 0
	s_mov_b32 m0, s30
	v_lshl_add_u64 v[248:249], s[52:53], 0, v[182:183]
	s_barrier
	ds_read_b128 v[114:117], v242 offset:16384
	ds_read_b128 v[130:133], v242 offset:17408
	ds_read_b128 v[134:137], v242 offset:18432
	ds_read_b128 v[146:149], v242 offset:19456
	ds_read_b128 v[172:175], v242 offset:20480
	ds_read_b128 v[190:193], v242 offset:21504
	ds_read_b128 v[194:197], v242 offset:22528
	ds_read_b128 v[198:201], v242 offset:23552
	global_load_lds_dwordx4 v[248:249], off
	v_lshl_add_u64 v[236:237], s[52:53], 0, v[178:179]
	s_mov_b32 m0, s54
	s_nop 0
	global_load_lds_dwordx4 v[236:237], off
	s_barrier
	s_waitcnt lgkmcnt(0)
	s_setprio 1
	s_waitcnt lgkmcnt(0)
	v_mfma_f32_16x16x32_bf16 v[94:97], v[42:45], v[114:117], v[94:97]
	v_mfma_f32_16x16x32_bf16 v[90:93], v[50:53], v[114:117], v[90:93]
	v_mfma_f32_16x16x32_bf16 v[78:81], v[42:45], v[134:137], v[78:81]
	v_mfma_f32_16x16x32_bf16 v[66:69], v[50:53], v[134:137], v[66:69]
	v_mfma_f32_16x16x32_bf16 v[30:33], v[42:45], v[172:175], v[30:33]
	v_mfma_f32_16x16x32_bf16 v[26:29], v[50:53], v[172:175], v[26:29]
	v_mfma_f32_16x16x32_bf16 v[14:17], v[42:45], v[194:197], v[14:17]
	v_mfma_f32_16x16x32_bf16 v[10:13], v[50:53], v[194:197], v[10:13]
	v_mfma_f32_16x16x32_bf16 v[94:97], v[46:49], v[130:133], v[94:97]
	v_mfma_f32_16x16x32_bf16 v[90:93], v[54:57], v[130:133], v[90:93]
	v_mfma_f32_16x16x32_bf16 v[78:81], v[46:49], v[146:149], v[78:81]
	v_mfma_f32_16x16x32_bf16 v[66:69], v[54:57], v[146:149], v[66:69]
	v_mfma_f32_16x16x32_bf16 v[30:33], v[46:49], v[190:193], v[30:33]
	v_mfma_f32_16x16x32_bf16 v[26:29], v[54:57], v[190:193], v[26:29]
	v_mfma_f32_16x16x32_bf16 v[14:17], v[46:49], v[198:201], v[14:17]
	v_mfma_f32_16x16x32_bf16 v[10:13], v[54:57], v[198:201], v[10:13]
	s_setprio 0
	s_barrier
; #define PG8_STAGE(bufoff, gbase, voff) do { _Pragma("unroll") for (int _i = 0; _i < 2; ++_i) \
;         __builtin_amdgcn_global_load_lds((const unsigned*)((const char*)(gbase) + (voff)[_i]), (LAS unsigned*)(lds + (bufoff) + ldsw + _i * 8192), 16, 0, 0); } while (0)
; #define PG8_LDA(dst, b, h) do { _Pragma("unroll") for (int m = 0; m < 4; ++m) _Pragma("unroll") for (int k = 0; k < 2; ++k) dst[m][k] = *(const LAS bf16x8*)(lds + PG8_SA(b, h) + aoff + m * 2048 + k * 1024); } while (0)
; #define PG8_LDB(dst, b, h) do { _Pragma("unroll") for (int n = 0; n < 2; ++n) _Pragma("unroll") for (int k = 0; k < 2; ++k) dst[n][k] = *(const LAS bf16x8*)(lds + PG8_SB(b, h) + boff + n * 2048 + k * 1024); } while (0)
; #define PG8_MMA(ai, bj, At, Bt) do { __builtin_amdgcn_s_setprio(1); _Pragma("unroll") for (int m = 0; m < 4; ++m) _Pragma("unroll") for (int n = 0; n < 2; ++n) _Pragma("unroll") for (int k = 0; k < 2; ++k) \
;         acc[ai][bj][m][n] = __builtin_amdgcn_mfma_f32_16x16x32_bf16(Bt[n][k], At[m][k], acc[ai][bj][m][n], 0, 0, 0); __builtin_amdgcn_s_setprio(0); } while (0)
; #define PG8_WAIT_V(n) asm volatile("s_waitcnt vmcnt(" #n ")" ::: "memory")
; #define PG8_WAIT_L(n) asm volatile("s_waitcnt lgkmcnt(" #n ")" ::: "memory")
; #define PG8_BAR __builtin_amdgcn_s_barrier()
; #define PG8_SCHED __builtin_amdgcn_sched_barrier(0)
; template <class Epi>
; __device__ __forceinline__ void gemm_phase(LAS unsigned char* lds, const Gemm g, const StaticOrder& S, const Epi& E) {
;     ...
;             PG8_STAGE(PG8_SB(0, 1), b2 + hstep, voffB);
;             PG8_WAIT_V(6); PG8_BAR; PG8_MMA(1, 1, At, B1); PG8_BAR;
;             PG8_LDB(B0, 1, 0); PG8_SCHED; PG8_LDA(At, 1, 0); PG8_STAGE(PG8_SA(0, 1), a2 + hstep, voffA);
;             PG8_WAIT_L(8); PG8_BAR; PG8_WAIT_L(0); PG8_MMA(0, 0, At, B0); PG8_BAR; PG8_SCHED;
;             PG8_LDB(B1, 1, 1); PG8_STAGE(PG8_SB(1, 0), b3, voffB);
;             PG8_BAR; PG8_WAIT_L(0); PG8_MMA(0, 1, At, B1); PG8_BAR;
;             PG8_LDA(At, 1, 1); PG8_STAGE(PG8_SA(1, 0), a3, voffA);
;             PG8_BAR; PG8_WAIT_L(0); PG8_MMA(1, 0, At, B0); PG8_BAR; PG8_SCHED;
	s_add_u32 s58, s36, 0x40000
	s_addc_u32 s59, s37, 0
	s_add_i32 s56, s56, s26
	v_lshl_add_u64 v[42:43], s[58:59], 0, v[180:181]
	s_mov_b32 m0, s56
	s_nop 0
	global_load_lds_dwordx4 v[42:43], off
	v_lshl_add_u64 v[42:43], s[58:59], 0, v[176:177]
	s_add_i32 m0, s56, 0x2000
	s_nop 0
	global_load_lds_dwordx4 v[42:43], off
	s_waitcnt vmcnt(6)
	s_barrier
	s_setprio 1
	v_mfma_f32_16x16x32_bf16 v[34:37], v[202:205], v[134:137], v[34:37]
	v_mfma_f32_16x16x32_bf16 v[38:41], v[210:213], v[134:137], v[38:41]
	v_mfma_f32_16x16x32_bf16 v[18:21], v[202:205], v[172:175], v[18:21]
	v_mfma_f32_16x16x32_bf16 v[22:25], v[210:213], v[172:175], v[22:25]
	v_mfma_f32_16x16x32_bf16 v[2:5], v[202:205], v[194:197], v[2:5]
	v_mfma_f32_16x16x32_bf16 v[6:9], v[210:213], v[194:197], v[6:9]
	v_mfma_f32_16x16x32_bf16 v[42:45], v[202:205], v[114:117], v[86:89]
	v_mfma_f32_16x16x32_bf16 v[46:49], v[210:213], v[114:117], v[82:85]
	v_mfma_f32_16x16x32_bf16 v[34:37], v[206:209], v[146:149], v[34:37]
	v_mfma_f32_16x16x32_bf16 v[38:41], v[214:217], v[146:149], v[38:41]
	v_mfma_f32_16x16x32_bf16 v[18:21], v[206:209], v[190:193], v[18:21]
	v_mfma_f32_16x16x32_bf16 v[22:25], v[214:217], v[190:193], v[22:25]
	v_mfma_f32_16x16x32_bf16 v[2:5], v[206:209], v[198:201], v[2:5]
	v_mfma_f32_16x16x32_bf16 v[6:9], v[214:217], v[198:201], v[6:9]
	v_mfma_f32_16x16x32_bf16 v[42:45], v[206:209], v[130:133], v[42:45]
	v_mfma_f32_16x16x32_bf16 v[46:49], v[214:217], v[130:133], v[46:49]
	s_setprio 0
	s_add_i32 s56, 0, 0x18000
	v_add_u32_e32 v0, s56, v171
	s_barrier
	ds_read_b128 v[50:53], v0
	ds_read_b128 v[54:57], v0 offset:1024
	ds_read_b128 v[82:85], v0 offset:2048
	ds_read_b128 v[86:89], v0 offset:3072
	s_add_u32 s52, s52, 0x40000
	s_addc_u32 s53, s53, 0
	s_mov_b32 m0, s55
	v_lshl_add_u64 v[146:147], s[52:53], 0, v[182:183]
	ds_read_b128 v[114:117], v242 offset:32768
	ds_read_b128 v[130:133], v242 offset:33792
	ds_read_b128 v[134:137], v242 offset:34816
	ds_read_b128 v[172:175], v242 offset:35840
	ds_read_b128 v[190:193], v242 offset:36864
	ds_read_b128 v[194:197], v242 offset:37888
	ds_read_b128 v[198:201], v242 offset:38912
	ds_read_b128 v[202:205], v242 offset:39936
	global_load_lds_dwordx4 v[146:147], off
	v_lshl_add_u64 v[146:147], s[52:53], 0, v[178:179]
	s_mov_b32 m0, s70
	s_nop 0
	global_load_lds_dwordx4 v[146:147], off
	s_waitcnt lgkmcnt(8)
	s_barrier
	s_waitcnt lgkmcnt(0)
	s_setprio 1
	s_waitcnt lgkmcnt(0)
	v_mfma_f32_16x16x32_bf16 v[146:149], v[50:53], v[114:117], v[158:161]
	v_mfma_f32_16x16x32_bf16 v[158:161], v[54:57], v[130:133], v[146:149]
	v_mfma_f32_16x16x32_bf16 v[146:149], v[82:85], v[114:117], v[154:157]
	v_mfma_f32_16x16x32_bf16 v[142:145], v[50:53], v[134:137], v[142:145]
	v_mfma_f32_16x16x32_bf16 v[138:141], v[82:85], v[134:137], v[138:141]
	v_mfma_f32_16x16x32_bf16 v[126:129], v[50:53], v[190:193], v[126:129]
	v_mfma_f32_16x16x32_bf16 v[122:125], v[82:85], v[190:193], v[122:125]
	v_mfma_f32_16x16x32_bf16 v[110:113], v[50:53], v[198:201], v[110:113]
	v_mfma_f32_16x16x32_bf16 v[106:109], v[82:85], v[198:201], v[106:109]
	v_mfma_f32_16x16x32_bf16 v[154:157], v[86:89], v[130:133], v[146:149]
	v_mfma_f32_16x16x32_bf16 v[142:145], v[54:57], v[172:175], v[142:145]
	v_mfma_f32_16x16x32_bf16 v[138:141], v[86:89], v[172:175], v[138:141]
	v_mfma_f32_16x16x32_bf16 v[126:129], v[54:57], v[194:197], v[126:129]
	v_mfma_f32_16x16x32_bf16 v[122:125], v[86:89], v[194:197], v[122:125]
	v_mfma_f32_16x16x32_bf16 v[110:113], v[54:57], v[202:205], v[110:113]
	v_mfma_f32_16x16x32_bf16 v[106:109], v[86:89], v[202:205], v[106:109]
	s_setprio 0
	s_barrier
	s_add_i32 s52, 0, 0x1c000
	s_add_i32 s53, s56, s26
	v_add_u32_e32 v0, s52, v171
	v_lshl_add_u64 v[146:147], v[222:223], 0, s[28:29]
	s_mov_b32 m0, s53
	ds_read_b128 v[206:209], v0
	ds_read_b128 v[210:213], v0 offset:1024
	ds_read_b128 v[214:217], v0 offset:2048
	ds_read_b128 v[218:221], v0 offset:3072
	global_load_lds_dwordx4 v[146:147], off
	v_lshl_add_u64 v[146:147], v[246:247], 0, s[28:29]
	s_add_i32 m0, s53, 0x2000
	s_nop 0
	global_load_lds_dwordx4 v[146:147], off
	s_barrier
	s_waitcnt lgkmcnt(0)
	s_setprio 1
	s_waitcnt lgkmcnt(0)
	v_mfma_f32_16x16x32_bf16 v[146:149], v[206:209], v[114:117], v[150:153]
	v_mfma_f32_16x16x32_bf16 v[58:61], v[214:217], v[114:117], v[58:61]
	v_mfma_f32_16x16x32_bf16 v[150:153], v[210:213], v[130:133], v[146:149]
	v_mfma_f32_16x16x32_bf16 v[146:149], v[218:221], v[130:133], v[58:61]
	v_mfma_f32_16x16x32_bf16 v[58:61], v[206:209], v[134:137], v[62:65]
	v_mfma_f32_16x16x32_bf16 v[130:133], v[210:213], v[172:175], v[58:61]
	v_mfma_f32_16x16x32_bf16 v[58:61], v[214:217], v[134:137], v[70:73]
	v_mfma_f32_16x16x32_bf16 v[134:137], v[218:221], v[172:175], v[58:61]
	v_mfma_f32_16x16x32_bf16 v[58:61], v[206:209], v[190:193], v[74:77]
	v_mfma_f32_16x16x32_bf16 v[114:117], v[210:213], v[194:197], v[58:61]
	v_mfma_f32_16x16x32_bf16 v[58:61], v[214:217], v[190:193], v[118:121]
	v_mfma_f32_16x16x32_bf16 v[118:121], v[218:221], v[194:197], v[58:61]
	v_mfma_f32_16x16x32_bf16 v[58:61], v[206:209], v[198:201], v[98:101]
	v_mfma_f32_16x16x32_bf16 v[98:101], v[210:213], v[202:205], v[58:61]
	v_mfma_f32_16x16x32_bf16 v[58:61], v[214:217], v[198:201], v[102:105]
	v_mfma_f32_16x16x32_bf16 v[102:105], v[218:221], v[202:205], v[58:61]
	s_setprio 0
	s_mov_b32 m0, s93
	v_lshl_add_u64 v[202:203], v[248:249], 0, s[28:29]
	s_barrier
	s_nop 2
	ds_read_b128 v[58:61], v242 offset:49152
	ds_read_b128 v[62:65], v242 offset:50176
	ds_read_b128 v[70:73], v242 offset:51200
	ds_read_b128 v[74:77], v242 offset:52224
	ds_read_b128 v[172:175], v242 offset:53248
	ds_read_b128 v[190:193], v242 offset:54272
	ds_read_b128 v[194:197], v242 offset:55296
	ds_read_b128 v[198:201], v242 offset:56320
	global_load_lds_dwordx4 v[202:203], off
	v_lshl_add_u64 v[202:203], v[236:237], 0, s[28:29]
	s_mov_b32 m0, s94
	s_nop 0
	global_load_lds_dwordx4 v[202:203], off
	s_barrier
; __device__ __forceinline__ float rstd_fix(u64 v) { return rsqrtf((float)v * (1.f / (1048576.f * 1024.f)) + 1e-6f); }
; #define PG8_STAGE(bufoff, gbase, voff) do { _Pragma("unroll") for (int _i = 0; _i < 2; ++_i) \
;         __builtin_amdgcn_global_load_lds((const unsigned*)((const char*)(gbase) + (voff)[_i]), (LAS unsigned*)(lds + (bufoff) + ldsw + _i * 8192), 16, 0, 0); } while (0)
; #define PG8_MMA(ai, bj, At, Bt) do { __builtin_amdgcn_s_setprio(1); _Pragma("unroll") for (int m = 0; m < 4; ++m) _Pragma("unroll") for (int n = 0; n < 2; ++n) _Pragma("unroll") for (int k = 0; k < 2; ++k) \
;         acc[ai][bj][m][n] = __builtin_amdgcn_mfma_f32_16x16x32_bf16(Bt[n][k], At[m][k], acc[ai][bj][m][n], 0, 0, 0); __builtin_amdgcn_s_setprio(0); } while (0)
; #define PG8_BAR __builtin_amdgcn_s_barrier()
; template <class Epi>
; __device__ __forceinline__ void gemm_phase(LAS unsigned char* lds, const Gemm g, const StaticOrder& S, const Epi& E) {
;     ...
;             PG8_BAR; PG8_WAIT_L(0); PG8_MMA(1, 0, At, B0); PG8_BAR; PG8_SCHED;
;             PG8_STAGE(PG8_SB(1, 1), b3 + hstep, voffB);
;             PG8_WAIT_V(6); PG8_BAR; PG8_MMA(1, 1, At, B1); PG8_BAR;
;     __device__ __forceinline__ void operator()(const f32x4 (&acc)[2][2][4][2], const Unit& u, int wr, int wc, int fr, int fq) const {
;         const int row0 = u.pm * BM + wr * 64 + fr, f0 = u.pn * HALF + wc * 32 + 8 * fq;
;         float w0[8], w1[8], w2[8], bb[8];
;         *(f32x4*)w0 = *(const f32x4*)(cw + f0); *(f32x4*)(w0 + 4) = *(const f32x4*)(cw + f0 + 4);
;         *(f32x4*)w1 = *(const f32x4*)(cw + DFF + f0); *(f32x4*)(w1 + 4) = *(const f32x4*)(cw + DFF + f0 + 4);
;         *(f32x4*)w2 = *(const f32x4*)(cw + 2 * DFF + f0); *(f32x4*)(w2 + 4) = *(const f32x4*)(cw + 2 * DFF + f0 + 4);
;         *(f32x4*)bb = *(const f32x4*)(cb + f0); *(f32x4*)(bb + 4) = *(const f32x4*)(cb + f0 + 4);
;         u64 rv[2][4];
; #pragma unroll
;         for (int ai = 0; ai < 2; ++ai)
; #pragma unroll
;             for (int m = 0; m < 4; ++m) rv[ai][m] = rss[row0 + ai * HALF + m * 16];
; #pragma unroll
;         for (int ai = 0; ai < 2; ++ai) {
;             float gp[8];
; #pragma unroll
;             for (int e = 0; e < 8; ++e) gp[e] = 0.f;
; #pragma unroll
;             for (int m = 0; m < 4; ++m) {
;                 const int row = row0 + ai * HALF + m * 16;
;                 const float rs = rstd_fix(rv[ai][m]);
	s_waitcnt lgkmcnt(0)
	s_setprio 1
	s_waitcnt lgkmcnt(0)
	v_mfma_f32_16x16x32_bf16 v[94:97], v[50:53], v[58:61], v[94:97]
	v_mfma_f32_16x16x32_bf16 v[90:93], v[82:85], v[58:61], v[90:93]
	v_mfma_f32_16x16x32_bf16 v[78:81], v[50:53], v[70:73], v[78:81]
	v_mfma_f32_16x16x32_bf16 v[66:69], v[82:85], v[70:73], v[66:69]
	v_mfma_f32_16x16x32_bf16 v[30:33], v[50:53], v[172:175], v[30:33]
	v_mfma_f32_16x16x32_bf16 v[26:29], v[82:85], v[172:175], v[26:29]
	v_mfma_f32_16x16x32_bf16 v[14:17], v[50:53], v[194:197], v[14:17]
	v_mfma_f32_16x16x32_bf16 v[10:13], v[82:85], v[194:197], v[10:13]
	v_mfma_f32_16x16x32_bf16 v[94:97], v[54:57], v[62:65], v[94:97]
	v_mfma_f32_16x16x32_bf16 v[90:93], v[86:89], v[62:65], v[90:93]
	v_mfma_f32_16x16x32_bf16 v[78:81], v[54:57], v[74:77], v[78:81]
	v_mfma_f32_16x16x32_bf16 v[66:69], v[86:89], v[74:77], v[66:69]
	v_mfma_f32_16x16x32_bf16 v[30:33], v[54:57], v[190:193], v[30:33]
	v_mfma_f32_16x16x32_bf16 v[26:29], v[86:89], v[190:193], v[26:29]
	v_mfma_f32_16x16x32_bf16 v[14:17], v[54:57], v[198:201], v[14:17]
	v_mfma_f32_16x16x32_bf16 v[10:13], v[86:89], v[198:201], v[10:13]
	s_setprio 0
	s_barrier
	s_add_u32 s36, s36, 0x40080
	s_addc_u32 s37, s37, 0
	s_add_i32 s52, s52, s26
	v_lshl_add_u64 v[50:51], s[36:37], 0, v[180:181]
	s_mov_b32 m0, s52
	s_nop 0
	global_load_lds_dwordx4 v[50:51], off
	v_lshl_add_u64 v[50:51], s[36:37], 0, v[176:177]
	s_add_i32 m0, s52, 0x2000
	s_nop 0
	global_load_lds_dwordx4 v[50:51], off
	s_waitcnt vmcnt(6)
	s_barrier
	s_setprio 1
	v_mfma_f32_16x16x32_bf16 v[42:45], v[206:209], v[58:61], v[42:45]
	v_mfma_f32_16x16x32_bf16 v[86:89], v[210:213], v[62:65], v[42:45]
	v_mfma_f32_16x16x32_bf16 v[42:45], v[214:217], v[58:61], v[46:49]
	v_mfma_f32_16x16x32_bf16 v[34:37], v[206:209], v[70:73], v[34:37]
	v_mfma_f32_16x16x32_bf16 v[38:41], v[214:217], v[70:73], v[38:41]
	v_mfma_f32_16x16x32_bf16 v[18:21], v[206:209], v[172:175], v[18:21]
	v_mfma_f32_16x16x32_bf16 v[22:25], v[214:217], v[172:175], v[22:25]
	v_mfma_f32_16x16x32_bf16 v[2:5], v[206:209], v[194:197], v[2:5]
	v_mfma_f32_16x16x32_bf16 v[6:9], v[214:217], v[194:197], v[6:9]
	v_mfma_f32_16x16x32_bf16 v[82:85], v[218:221], v[62:65], v[42:45]
	v_mfma_f32_16x16x32_bf16 v[34:37], v[210:213], v[74:77], v[34:37]
	v_mfma_f32_16x16x32_bf16 v[38:41], v[218:221], v[74:77], v[38:41]
	v_mfma_f32_16x16x32_bf16 v[18:21], v[210:213], v[190:193], v[18:21]
	v_mfma_f32_16x16x32_bf16 v[22:25], v[218:221], v[190:193], v[22:25]
	v_mfma_f32_16x16x32_bf16 v[2:5], v[210:213], v[198:201], v[2:5]
	v_mfma_f32_16x16x32_bf16 v[6:9], v[218:221], v[198:201], v[6:9]
	s_setprio 0
	s_add_i32 s24, s24, 2
	s_add_u32 s0, s0, 0x100
	s_addc_u32 s1, s1, 0
	s_add_u32 vcc_lo, vcc_lo, 0x100
	s_addc_u32 vcc_hi, vcc_hi, 0
	s_cmp_gt_u32 s24, 13
	s_barrier
	s_cbranch_scc0 .LBB0_211
	s_lshl_b32 s2, s2, 8
	s_add_i32 s2, s2, s71
	v_lshl_or_b32 v190, s3, 7, v241
	v_or_b32_e32 v196, s2, v168
	v_ashrrev_i32_e32 v191, 31, v190
	v_ashrrev_i32_e32 v197, 31, v196
	s_and_b32 s24, s95, 1
	s_lshl_b32 s24, s24, 12
	s_add_i32 s24, s24, 0x20400
	v_lshl_add_u32 v173, v241, 2, s24
	v_add_lshl_u32 v172, s71, v168, 3
	v_add_u32_e32 v172, s24, v172
	ds_read_b128 v[42:45], v173
	ds_read_b128 v[58:61], v173 offset:16
	ds_read_b128 v[46:49], v173 offset:512
	ds_read_b128 v[62:65], v173 offset:528
	ds_read_b128 v[50:53], v173 offset:1024
	ds_read_b128 v[70:73], v173 offset:1040
	ds_read_b128 v[54:57], v173 offset:1536
	ds_read_b128 v[74:77], v173 offset:1552
	ds_read_b64 v[174:175], v172 offset:2048
	ds_read_b64 v[206:207], v172 offset:2176
	ds_read_b64 v[204:205], v172 offset:2304
	ds_read_b64 v[202:203], v172 offset:2432
	ds_read_b64 v[200:201], v172 offset:3072
	ds_read_b64 v[198:199], v172 offset:3200
	ds_read_b64 v[194:195], v172 offset:3328
	ds_read_b64 v[192:193], v172 offset:3456
	v_mov_b32_e32 v217, v1
	v_mov_b32_e32 v219, v1
	s_waitcnt lgkmcnt(0)
	v_ffbh_u32_e32 v0, v175
	v_min_u32_e32 v0, 32, v0
	v_lshlrev_b64 v[172:173], v0, v[174:175]
	v_min_u32_e32 v172, 1, v172
	v_or_b32_e32 v172, v173, v172
	v_cvt_f32_u32_e32 v172, v172
	v_sub_u32_e32 v0, 32, v0
	v_mov_b32_dpp v217, v217 row_ror:1 row_mask:0xf bank_mask:0xf
	v_mov_b32_dpp v219, v219 row_ror:2 row_mask:0xf bank_mask:0xf
	v_ldexp_f32 v0, v172, v0
	v_fmamk_f32 v0, v0, 0x30800000, v162
	v_cmp_gt_f32_e32 vcc, s79, v0
	v_mul_f32_e32 v172, 0x4b800000, v0
	v_mov_b32_e32 v212, v217
	v_cndmask_b32_e32 v0, v0, v172, vcc
	v_rsq_f32_e32 v0, v0
	v_mov_b32_e32 v213, v217
	v_mov_b32_e32 v214, v219
	v_mov_b32_e32 v215, v219
	v_mul_f32_e32 v172, 0x45800000, v0
	v_cndmask_b32_e32 v0, v0, v172, vcc
	v_pk_mul_f32 v[158:159], v[158:159], v[0:1] op_sel_hi:[1,0]
	v_pk_mul_f32 v[154:155], v[154:155], v[0:1] op_sel_hi:[1,0]
	v_pk_mul_f32 v[208:209], v[150:151], v[0:1] op_sel_hi:[1,0]
	v_pk_mul_f32 v[210:211], v[146:147], v[0:1] op_sel_hi:[1,0]
	v_pk_mul_f32 v[150:151], v[160:161], v[0:1] op_sel_hi:[1,0]
	v_pk_mul_f32 v[146:147], v[156:157], v[0:1] op_sel_hi:[1,0]
	v_mov_b32_e32 v156, v217
	v_mov_b32_e32 v157, v217
	v_mov_b32_e32 v160, v219
	v_mov_b32_e32 v161, v219
	v_mov_b32_e32 v220, v217
	v_mov_b32_e32 v221, v217
	v_mov_b32_e32 v222, v219
	v_mov_b32_e32 v223, v219
	v_mov_b32_e32 v216, v217
	v_mov_b32_e32 v218, v219
	v_pk_mul_f32 v[152:153], v[152:153], v[0:1] op_sel_hi:[1,0]
	v_pk_mul_f32 v[148:149], v[148:149], v[0:1] op_sel_hi:[1,0]
	v_mov_b32_dpp v156, v158 row_shr:1 row_mask:0xf bank_mask:0xf
	v_mov_b32_dpp v157, v159 row_shr:1 row_mask:0xf bank_mask:0xf
	v_mov_b32_dpp v160, v158 row_shr:2 row_mask:0xf bank_mask:0xf
	v_mov_b32_dpp v161, v159 row_shr:2 row_mask:0xf bank_mask:0xf
	v_mov_b32_dpp v212, v150 row_shr:1 row_mask:0xf bank_mask:0xf
	v_mov_b32_dpp v213, v151 row_shr:1 row_mask:0xf bank_mask:0xf
	v_mov_b32_dpp v214, v150 row_shr:2 row_mask:0xf bank_mask:0xf
	v_mov_b32_dpp v215, v151 row_shr:2 row_mask:0xf bank_mask:0xf
	v_mov_b32_dpp v220, v154 row_shr:1 row_mask:0xf bank_mask:0xf
	v_mov_b32_dpp v221, v155 row_shr:1 row_mask:0xf bank_mask:0xf
	v_mov_b32_dpp v222, v154 row_shr:2 row_mask:0xf bank_mask:0xf
	v_mov_b32_dpp v223, v155 row_shr:2 row_mask:0xf bank_mask:0xf
	v_mov_b32_dpp v216, v146 row_shr:1 row_mask:0xf bank_mask:0xf
	v_mov_b32_dpp v217, v147 row_shr:1 row_mask:0xf bank_mask:0xf
	v_mov_b32_dpp v218, v146 row_shr:2 row_mask:0xf bank_mask:0xf
	v_mov_b32_dpp v219, v147 row_shr:2 row_mask:0xf bank_mask:0xf
	s_and_saveexec_b64 s[0:1], s[40:41]
	s_xor_b64 s[0:1], exec, s[0:1]
	s_cbranch_execz .LBB0_214
; __device__ __forceinline__ u32x4 pack8(const float* f) { u32x4 w; w.x = pk2(f[0], f[1]); w.y = pk2(f[2], f[3]); w.z = pk2(f[4], f[5]); w.w = pk2(f[6], f[7]); return w; }
; template <int N> __device__ __forceinline__ float dpp_shr(float old, float src) { return __int_as_float(__builtin_amdgcn_update_dpp(__float_as_int(old), __float_as_int(src), 0x110 + N, 0xf, 0xf, false)); }
; template <int N> __device__ __forceinline__ float dpp_ror(float src) { return __int_as_float(__builtin_amdgcn_update_dpp(0, __float_as_int(src), 0x120 + N, 0xf, 0xf, false)); }
;     __device__ __forceinline__ void operator()(const f32x4 (&acc)[2][2][4][2], const Unit& u, int wr, int wc, int fr, int fq) const {
;     ...
;                 for (int e2 = 0; e2 < 4; ++e2) {
;                     const int e = 2 * e2;
;                     const f32x2 gv = {g[e], g[e + 1]};
;                     const f32x2 g1v = {dpp_shr<1>(dpp_ror<1>(gp[e]), g[e]), dpp_shr<1>(dpp_ror<1>(gp[e + 1]), g[e + 1])};
;                     const f32x2 g2v = {dpp_shr<2>(dpp_ror<2>(gp[e]), g[e]), dpp_shr<2>(dpp_ror<2>(gp[e + 1]), g[e + 1])};
;                     const f32x2 w0v = {w0[e], w0[e + 1]}, w1v = {w1[e], w1[e + 1]}, w2v = {w2[e], w2[e + 1]}, bbv = {bb[e], bb[e + 1]}, upv = {up[e], up[e + 1]};
;                     const f32x2 y = __builtin_elementwise_fma(w0v, g2v, __builtin_elementwise_fma(w1v, g1v, __builtin_elementwise_fma(w2v, gv, bbv)));
;                     const f32x2 z = y * __builtin_elementwise_fma(y * y, (f32x2){0.1029432397f, 0.1029432397f}, (f32x2){2.302208198f, 2.302208198f});
;                     f32x2 d; d.x = __builtin_amdgcn_exp2f(z.x); d.y = __builtin_amdgcn_exp2f(z.y);
;                     d = d + 1.0f;
;                     f32x2 r; r.x = __builtin_amdgcn_rcpf(d.x); r.y = __builtin_amdgcn_rcpf(d.y);
;                     const f32x2 ov = __builtin_elementwise_fma(-y, r, y) * upv;
;                     o[e] = ov.x; o[e + 1] = ov.y;
;                 }
;                 if (m == 0 && fr < 2) {
;                     const size_t so = ((size_t)(row >> 6) * 2 + fr) * DFF + f0;
;                     *(u32x4*)(gs01 + so) = pack8(g); *(u32x4*)(us01 + so) = pack8(up);
;                 } else *(u32x4*)(act + (size_t)row * DFF + f0) = pack8(o);
	v_pk_fma_f32 v[172:173], v[72:73], v[146:147], v[76:77]
	s_mov_b32 s24, 0x40135761
	v_pk_fma_f32 v[172:173], v[64:65], v[216:217], v[172:173]
	v_mov_b64_e32 v[216:217], s[24:25]
	v_pk_fma_f32 v[172:173], v[60:61], v[218:219], v[172:173]
	s_mov_b32 s24, 0x3dd2d3e8
	v_pk_mul_f32 v[174:175], v[172:173], v[172:173]
	v_readlane_b32 s36, v252, 57
	v_pk_fma_f32 v[174:175], v[174:175], s[24:25], v[216:217] op_sel_hi:[1,0,0]
	v_readlane_b32 s37, v252, 58
	v_pk_mul_f32 v[174:175], v[172:173], v[174:175]
	s_movk_i32 s3, 0x1600
	v_exp_f32_e32 v174, v174
	v_exp_f32_e32 v175, v175
	s_nop 0
	v_pk_add_f32 v[174:175], v[174:175], 1.0 op_sel_hi:[1,0]
	s_nop 0
	v_rcp_f32_e32 v174, v174
	v_rcp_f32_e32 v175, v175
	s_nop 0
	v_pk_fma_f32 v[172:173], v[172:173], v[174:175], v[172:173] neg_lo:[1,0,0] neg_hi:[1,0,0]
	s_nop 0
	v_pk_mul_f32 v[148:149], v[148:149], v[172:173]
	v_pk_fma_f32 v[172:173], v[70:71], v[154:155], v[74:75]
	s_nop 0
	v_pk_fma_f32 v[172:173], v[62:63], v[220:221], v[172:173]
	s_nop 0
	v_pk_fma_f32 v[172:173], v[58:59], v[222:223], v[172:173]
	s_nop 0
	v_pk_mul_f32 v[174:175], v[172:173], v[172:173]
	s_nop 0
	v_pk_fma_f32 v[174:175], v[174:175], s[24:25], v[216:217] op_sel_hi:[1,0,0]
	s_nop 0
	v_pk_mul_f32 v[174:175], v[172:173], v[174:175]
	s_nop 0
	v_exp_f32_e32 v174, v174
	v_exp_f32_e32 v175, v175
	s_nop 0
	v_pk_add_f32 v[174:175], v[174:175], 1.0 op_sel_hi:[1,0]
	s_nop 0
	v_rcp_f32_e32 v174, v174
	v_rcp_f32_e32 v175, v175
	s_nop 0
	v_pk_fma_f32 v[172:173], v[172:173], v[174:175], v[172:173] neg_lo:[1,0,0] neg_hi:[1,0,0]
	s_nop 0
	v_pk_mul_f32 v[174:175], v[210:211], v[172:173]
	v_pk_fma_f32 v[172:173], v[52:53], v[150:151], v[56:57]
	s_nop 0
	v_pk_fma_f32 v[172:173], v[48:49], v[212:213], v[172:173]
	s_nop 0
	v_pk_fma_f32 v[172:173], v[44:45], v[214:215], v[172:173]
	s_nop 0
	v_pk_mul_f32 v[210:211], v[172:173], v[172:173]
	s_nop 0
	v_pk_fma_f32 v[210:211], v[210:211], s[24:25], v[216:217] op_sel_hi:[1,0,0]
	s_nop 0
	v_pk_mul_f32 v[210:211], v[172:173], v[210:211]
	s_nop 0
	v_exp_f32_e32 v210, v210
	v_exp_f32_e32 v211, v211
	s_nop 0
	v_pk_add_f32 v[210:211], v[210:211], 1.0 op_sel_hi:[1,0]
	s_nop 0
	v_rcp_f32_e32 v210, v210
	v_rcp_f32_e32 v211, v211
	s_nop 0
	v_pk_fma_f32 v[172:173], v[172:173], v[210:211], v[172:173] neg_lo:[1,0,0] neg_hi:[1,0,0]
	s_nop 0
	v_pk_mul_f32 v[152:153], v[152:153], v[172:173]
	v_pk_fma_f32 v[172:173], v[50:51], v[158:159], v[54:55]
	s_nop 0
	v_pk_fma_f32 v[156:157], v[46:47], v[156:157], v[172:173]
	s_nop 0
	v_pk_fma_f32 v[156:157], v[42:43], v[160:161], v[156:157]
	s_nop 0
	v_pk_mul_f32 v[160:161], v[156:157], v[156:157]
	s_nop 0
	v_pk_fma_f32 v[160:161], v[160:161], s[24:25], v[216:217] op_sel_hi:[1,0,0]
	s_nop 0
	v_pk_mul_f32 v[160:161], v[156:157], v[160:161]
	s_nop 0
	v_exp_f32_e32 v160, v160
	v_exp_f32_e32 v161, v161
	s_nop 0
	v_pk_add_f32 v[160:161], v[160:161], 1.0 op_sel_hi:[1,0]
	s_nop 0
	v_rcp_f32_e32 v160, v160
	v_rcp_f32_e32 v161, v161
	s_nop 0
	v_pk_fma_f32 v[156:157], v[156:157], v[160:161], v[156:157] neg_lo:[1,0,0] neg_hi:[1,0,0]
	s_nop 0
	v_pk_mul_f32 v[156:157], v[208:209], v[156:157]
	s_nop 0
	v_cvt_pk_bf16_f32 v172, v156, v157
	v_cvt_pk_bf16_f32 v173, v152, v153
	v_cvt_pk_bf16_f32 v174, v174, v175
	v_cvt_pk_bf16_f32 v175, v148, v149
	v_mov_b64_e32 v[148:149], s[36:37]
	v_mad_i64_i32 v[148:149], s[36:37], v196, s3, v[148:149]
	v_lshl_add_u64 v[148:149], v[190:191], 1, v[148:149]
	global_store_dwordx4 v[148:149], v[172:175], off

; __global__ void __launch_bounds__(512, 2) mega(Params p, int ph0, int ph1, int coop) {
;     extern __shared__ __attribute__((aligned(16))) unsigned char shm[];
	.amdhsa_kernel _Z4mega6Paramsiii
		.amdhsa_group_segment_fixed_size 12288
		.amdhsa_private_segment_fixed_size 0
		.amdhsa_kernarg_size 536
		.amdhsa_user_sgpr_count 2
		.amdhsa_user_sgpr_dispatch_ptr 0
		.amdhsa_user_sgpr_queue_ptr 0
		.amdhsa_user_sgpr_kernarg_segment_ptr 1
		.amdhsa_user_sgpr_dispatch_id 0
		.amdhsa_user_sgpr_kernarg_preload_length 0
		.amdhsa_user_sgpr_kernarg_preload_offset 0
		.amdhsa_user_sgpr_private_segment_size 0
		.amdhsa_uses_dynamic_stack 0
		.amdhsa_enable_private_segment 0
		.amdhsa_system_sgpr_workgroup_id_x 1
		.amdhsa_system_sgpr_workgroup_id_y 0
		.amdhsa_system_sgpr_workgroup_id_z 0
		.amdhsa_system_sgpr_workgroup_info 0
		.amdhsa_system_vgpr_workitem_id 2
		.amdhsa_next_free_vgpr 256
		.amdhsa_next_free_sgpr 100
		.amdhsa_accum_offset 256
		.amdhsa_reserve_vcc 1
		.amdhsa_float_round_mode_32 0
		.amdhsa_float_round_mode_16_64 0
		.amdhsa_float_denorm_mode_32 3
		.amdhsa_float_denorm_mode_16_64 3
		.amdhsa_dx10_clamp 1
		.amdhsa_ieee_mode 1
		.amdhsa_fp16_overflow 0
		.amdhsa_tg_split 0
		.amdhsa_exception_fp_ieee_invalid_op 0
		.amdhsa_exception_fp_denorm_src 0
		.amdhsa_exception_fp_ieee_div_zero 0
		.amdhsa_exception_fp_ieee_overflow 0
		.amdhsa_exception_fp_ieee_underflow 0
		.amdhsa_exception_fp_ieee_inexact 0
		.amdhsa_exception_int_div_zero 0
	.end_amdhsa_kernel

; __global__ void __launch_bounds__(512, 2) mega(Params p, int ph0, int ph1, int coop) {
;     extern __shared__ __attribute__((aligned(16))) unsigned char shm[];
amdhsa.kernels:
  - .agpr_count:     0
    .args:
      - .offset:         0
        .size:           264
        .value_kind:     by_value
      - .offset:         264
        .size:           4
        .value_kind:     by_value
      - .offset:         268
        .size:           4
        .value_kind:     by_value
      - .offset:         272
        .size:           4
        .value_kind:     by_value
      - .offset:         280
        .size:           4
        .value_kind:     hidden_block_count_x
      - .offset:         284
        .size:           4
        .value_kind:     hidden_block_count_y
      - .offset:         288
        .size:           4
        .value_kind:     hidden_block_count_z
      - .offset:         292
        .size:           2
        .value_kind:     hidden_group_size_x
      - .offset:         294
        .size:           2
        .value_kind:     hidden_group_size_y
      - .offset:         296
        .size:           2
        .value_kind:     hidden_group_size_z
      - .offset:         298
        .size:           2
        .value_kind:     hidden_remainder_x
      - .offset:         300
        .size:           2
        .value_kind:     hidden_remainder_y
      - .offset:         302
        .size:           2
        .value_kind:     hidden_remainder_z
      - .offset:         320
        .size:           8
        .value_kind:     hidden_global_offset_x
      - .offset:         328
        .size:           8
        .value_kind:     hidden_global_offset_y
      - .offset:         336
        .size:           8
        .value_kind:     hidden_global_offset_z
      - .offset:         344
        .size:           2
        .value_kind:     hidden_grid_dims
      - .offset:         368
        .size:           8
        .value_kind:     hidden_multigrid_sync_arg
      - .offset:         400
        .size:           4
        .value_kind:     hidden_dynamic_lds_size
    .group_segment_fixed_size: 12288
    .kernarg_segment_align: 8
    .kernarg_segment_size: 536
    .language:       OpenCL C
    .language_version:
      - 2
      - 0
    .max_flat_workgroup_size: 512
    .name:           _Z4mega6Paramsiii
    .private_segment_fixed_size: 0
    .sgpr_count:     106
    .sgpr_spill_count: 390
    .symbol:         _Z4mega6Paramsiii.kd
    .uniform_work_group_size: 1
    .uses_dynamic_stack: false
    .vgpr_count:     256
    .vgpr_spill_count: 0
    .wavefront_size: 64
